# rglru gate segment rewritten with packed f32 math (bit-identical) on top of v19
# baseline (speedup 1.0000x reference)
; #define LAS __attribute__((address_space(3)))
; __device__ __forceinline__ float fsigmoid(float x) { return __builtin_amdgcn_rcpf(1.0f + __builtin_amdgcn_exp2f(-1.4426950408889634f * x)); }
; __device__ __forceinline__ void rglru_unit(LAS unsigned char* lds, int unit, const bf16* PBp, bf16* MGp, float* SSQRp, const float* cw, const float* cbias, const float* wa, const float* ba, const float* wx, const float* bxp, const float* lam) {
;     ...
;         {
;             typedef float f32x4m __attribute__((ext_vector_type(4)));
;             const rg_bf16x8 a0 = *(const LAS rg_bf16x8*)(XRB + (wave * 16 + fr) * 72 + 8 * fq), a1 = *(const LAS rg_bf16x8*)(XRB + (wave * 16 + fr) * 72 + 32 + 8 * fq);
;             f32x4m d[4];
; #pragma unroll
;             for (int nb = 0; nb < 4; ++nb) { d[nb] = (f32x4m){0.f, 0.f, 0.f, 0.f};
;                 d[nb] = __builtin_amdgcn_mfma_f32_16x16x32_bf16(a0, wb[nb][0], d[nb], 0, 0, 0); d[nb] = __builtin_amdgcn_mfma_f32_16x16x32_bf16(a1, wb[nb][1], d[nb], 0, 0, 0); }
; #pragma unroll
;             for (int cb = 0; cb < 2; ++cb)
; #pragma unroll
;                 for (int e = 0; e < 4; ++e) {
;                     const int tok = wave * 16 + 4 * fq + e, cl = 16 * cb + fr;
;                     const float r = fsigmoid(d[cb][e] + gba[cb]), ig = fsigmoid(d[2 + cb][e] + gbx[cb]);
;                     const float a = __builtin_amdgcn_exp2f(r * gsp[cb]);
;                     const float om = fmaxf(1.0f - a * a, 0.0f);
;                     AL[tok * 32 + cl] = a; UL[tok * 32 + cl] = __builtin_amdgcn_sqrtf(om) * (ig * XRF[tok * 32 + cl]);
;                 }
;         }
.LBB0_452:
	s_waitcnt lgkmcnt(0)
	s_barrier
	ds_read_b128 v[72:75], v134
	ds_read_b128 v[76:79], v134 offset:64
	v_add_u32_e32 v1, 0x4800, v138
	ds_read2_b32 v[92:93], v1 offset1:32
	ds_read2_b32 v[94:95], v1 offset0:64 offset1:96
	ds_read2_b32 v[96:97], v1 offset0:16 offset1:48
	ds_read2_b32 v[98:99], v1 offset0:80 offset1:112
	v_mov_b32_e32 v2, 0xbfb8aa3b
	v_mov_b32_e32 v120, 1.0
	v_mov_b32_e32 v112, v123
	v_mov_b32_e32 v114, v125
	v_mov_b32_e32 v116, v127
	s_waitcnt lgkmcnt(4)
	v_mfma_f32_16x16x32_bf16 v[80:83], v[72:75], v[20:23], 0
	v_mfma_f32_16x16x32_bf16 v[84:87], v[72:75], v[52:55], 0
	v_mfma_f32_16x16x32_bf16 v[88:91], v[72:75], v[36:39], 0
	v_mfma_f32_16x16x32_bf16 v[108:111], v[72:75], v[60:63], 0
	v_mfma_f32_16x16x32_bf16 v[80:83], v[76:79], v[32:35], v[80:83]
	v_mfma_f32_16x16x32_bf16 v[84:87], v[76:79], v[56:59], v[84:87]
	v_mfma_f32_16x16x32_bf16 v[88:91], v[76:79], v[48:51], v[88:91]
	v_mfma_f32_16x16x32_bf16 v[108:111], v[76:79], v[64:67], v[108:111]
	v_add_u32_e32 v74, 0x8800, v138
	v_add_u32_e32 v75, 0xc800, v138
	s_nop 7
	s_nop 3
	s_waitcnt lgkmcnt(0)
	v_pk_add_f32 v[80:81], v[80:81], v[122:123] op_sel_hi:[1,0]
	v_pk_add_f32 v[84:85], v[84:85], v[112:113] op_sel_hi:[1,0]
	v_pk_mul_f32 v[80:81], v[80:81], v[2:3] op_sel_hi:[1,0]
	v_pk_mul_f32 v[84:85], v[84:85], v[2:3] op_sel_hi:[1,0]
	v_exp_f32_e32 v80, v80
	v_exp_f32_e32 v81, v81
	v_exp_f32_e32 v84, v84
	v_exp_f32_e32 v85, v85
	v_pk_add_f32 v[80:81], v[80:81], v[120:121] op_sel_hi:[1,0]
	v_pk_add_f32 v[84:85], v[84:85], v[120:121] op_sel_hi:[1,0]
	v_rcp_f32_e32 v80, v80
	v_rcp_f32_e32 v81, v81
	v_rcp_f32_e32 v84, v84
	v_rcp_f32_e32 v85, v85
	v_pk_mul_f32 v[118:119], v[80:81], v[128:129] op_sel_hi:[1,0]
	v_pk_mul_f32 v[78:79], v[92:93], v[84:85]
	v_exp_f32_e32 v118, v118
	v_exp_f32_e32 v119, v119
	s_nop 0
	v_fma_f32 v76, -v118, v118, 1.0
	v_fma_f32 v77, -v119, v119, 1.0
	v_max_f32_e32 v76, 0, v76
	v_max_f32_e32 v77, 0, v77
	v_sqrt_f32_e32 v76, v76
	v_sqrt_f32_e32 v77, v77
	ds_write2_b32 v74, v118, v119 offset0:0 offset1:32
	v_pk_mul_f32 v[78:79], v[78:79], v[76:77]
	ds_write2_b32 v75, v78, v79 offset0:0 offset1:32
	v_pk_add_f32 v[82:83], v[82:83], v[122:123] op_sel_hi:[1,0]
	v_pk_add_f32 v[86:87], v[86:87], v[112:113] op_sel_hi:[1,0]
	v_pk_mul_f32 v[82:83], v[82:83], v[2:3] op_sel_hi:[1,0]
	v_pk_mul_f32 v[86:87], v[86:87], v[2:3] op_sel_hi:[1,0]
	v_exp_f32_e32 v82, v82
	v_exp_f32_e32 v83, v83
	v_exp_f32_e32 v86, v86
	v_exp_f32_e32 v87, v87
	v_pk_add_f32 v[82:83], v[82:83], v[120:121] op_sel_hi:[1,0]
	v_pk_add_f32 v[86:87], v[86:87], v[120:121] op_sel_hi:[1,0]
	v_rcp_f32_e32 v82, v82
	v_rcp_f32_e32 v83, v83
	v_rcp_f32_e32 v86, v86
	v_rcp_f32_e32 v87, v87
	v_pk_mul_f32 v[118:119], v[82:83], v[128:129] op_sel_hi:[1,0]
	v_pk_mul_f32 v[78:79], v[94:95], v[86:87]
	v_exp_f32_e32 v118, v118
	v_exp_f32_e32 v119, v119
	s_nop 0
	v_fma_f32 v76, -v118, v118, 1.0
	v_fma_f32 v77, -v119, v119, 1.0
	v_max_f32_e32 v76, 0, v76
	v_max_f32_e32 v77, 0, v77
	v_sqrt_f32_e32 v76, v76
	v_sqrt_f32_e32 v77, v77
	ds_write2_b32 v74, v118, v119 offset0:64 offset1:96
	v_pk_mul_f32 v[78:79], v[78:79], v[76:77]
	ds_write2_b32 v75, v78, v79 offset0:64 offset1:96
	v_pk_add_f32 v[88:89], v[88:89], v[124:125] op_sel_hi:[1,0]
	v_pk_add_f32 v[108:109], v[108:109], v[114:115] op_sel_hi:[1,0]
	v_pk_mul_f32 v[88:89], v[88:89], v[2:3] op_sel_hi:[1,0]
	v_pk_mul_f32 v[108:109], v[108:109], v[2:3] op_sel_hi:[1,0]
	v_exp_f32_e32 v88, v88
	v_exp_f32_e32 v89, v89
	v_exp_f32_e32 v108, v108
	v_exp_f32_e32 v109, v109
	v_pk_add_f32 v[88:89], v[88:89], v[120:121] op_sel_hi:[1,0]
	v_pk_add_f32 v[108:109], v[108:109], v[120:121] op_sel_hi:[1,0]
	v_rcp_f32_e32 v88, v88
	v_rcp_f32_e32 v89, v89
	v_rcp_f32_e32 v108, v108
	v_rcp_f32_e32 v109, v109
	v_pk_mul_f32 v[118:119], v[88:89], v[116:117] op_sel_hi:[1,0]
	v_pk_mul_f32 v[78:79], v[96:97], v[108:109]
	v_exp_f32_e32 v118, v118
	v_exp_f32_e32 v119, v119
	s_nop 0
	v_fma_f32 v76, -v118, v118, 1.0
	v_fma_f32 v77, -v119, v119, 1.0
	v_max_f32_e32 v76, 0, v76
	v_max_f32_e32 v77, 0, v77
	v_sqrt_f32_e32 v76, v76
	v_sqrt_f32_e32 v77, v77
	ds_write2_b32 v74, v118, v119 offset0:16 offset1:48
	v_pk_mul_f32 v[78:79], v[78:79], v[76:77]
	ds_write2_b32 v75, v78, v79 offset0:16 offset1:48
	v_pk_add_f32 v[90:91], v[90:91], v[124:125] op_sel_hi:[1,0]
	v_pk_add_f32 v[110:111], v[110:111], v[114:115] op_sel_hi:[1,0]
	v_pk_mul_f32 v[90:91], v[90:91], v[2:3] op_sel_hi:[1,0]
	v_pk_mul_f32 v[110:111], v[110:111], v[2:3] op_sel_hi:[1,0]
	v_exp_f32_e32 v90, v90
	v_exp_f32_e32 v91, v91
	v_exp_f32_e32 v110, v110
	v_exp_f32_e32 v111, v111
	v_pk_add_f32 v[90:91], v[90:91], v[120:121] op_sel_hi:[1,0]
	v_pk_add_f32 v[110:111], v[110:111], v[120:121] op_sel_hi:[1,0]
	v_rcp_f32_e32 v90, v90
	v_rcp_f32_e32 v91, v91
	v_rcp_f32_e32 v110, v110
	v_rcp_f32_e32 v111, v111
	v_pk_mul_f32 v[118:119], v[90:91], v[116:117] op_sel_hi:[1,0]
	v_pk_mul_f32 v[78:79], v[98:99], v[110:111]
	v_exp_f32_e32 v118, v118
	v_exp_f32_e32 v119, v119
	s_nop 0
	v_fma_f32 v76, -v118, v118, 1.0
	v_fma_f32 v77, -v119, v119, 1.0
	v_max_f32_e32 v76, 0, v76
	v_max_f32_e32 v77, 0, v77
	v_sqrt_f32_e32 v76, v76
	v_sqrt_f32_e32 v77, v77
	ds_write2_b32 v74, v118, v119 offset0:80 offset1:112
	v_pk_mul_f32 v[78:79], v[78:79], v[76:77]
	ds_write2_b32 v75, v78, v79 offset0:80 offset1:112
	v_add_u32_e32 v1, 0x8800, v140
	s_waitcnt lgkmcnt(0)
	s_barrier
; #define LAS __attribute__((address_space(3)))
; __device__ __forceinline__ void rglru_unit(LAS unsigned char* lds, int unit, const bf16* PBp, bf16* MGp, float* SSQRp, const float* cw, const float* cbias, const float* wa, const float* ba, const float* wx, const float* bxp, const float* lam) {
;     ...
;         float av[8], uv[8];
; #pragma unroll
;         for (int k = 0; k < 8; ++k) { av[k] = AL[(ss * 8 + k) * 32 + sc]; uv[k] = UL[(ss * 8 + k) * 32 + sc]; }
;         { float h = 0.f, p = 1.f;
; #pragma unroll
;           for (int k = 0; k < 8; ++k) { h = av[k] * h + uv[k]; p *= av[k]; }
;           PE[(ss * 32 + sc) * 2] = p; PE[(ss * 32 + sc) * 2 + 1] = h; }
;         __syncthreads();
;         float h = HIN[sc];
;         { typedef float f32x2v __attribute__((ext_vector_type(2))); f32x2v pe[15];
; #pragma unroll
;           for (int s2 = 0; s2 < 15; ++s2) pe[s2] = *(const LAS f32x2v*)(PE + (s2 * 32 + sc) * 2);
; #pragma unroll
;           for (int s2 = 0; s2 < 15; ++s2) h = (s2 < ss) ? fmaf(pe[s2].x, h, pe[s2].y) : h; }
	ds_read2_b32 v[120:121], v1 offset1:32
	v_add_u32_e32 v2, 0xc800, v140
	ds_read2_b32 v[118:119], v2 offset1:32
	ds_read2_b32 v[116:117], v1 offset0:64 offset1:96
	ds_read2_b32 v[114:115], v2 offset0:64 offset1:96
	ds_read2_b32 v[112:113], v1 offset0:128 offset1:160
	ds_read2_b32 v[110:111], v2 offset0:128 offset1:160
	ds_read2_b32 v[108:109], v1 offset0:192 offset1:224
	ds_read2_b32 v[2:3], v2 offset0:192 offset1:224
	s_waitcnt lgkmcnt(5)
	v_mov_b32_e32 v74, v116
	s_waitcnt lgkmcnt(3)
	v_mov_b32_e32 v75, v113
	v_fma_f32 v1, 0, v120, v118
	v_fma_f32 v1, v1, v121, v119
	v_fma_f32 v1, v1, v116, v114
	v_fma_f32 v1, v1, v117, v115
	v_mul_f32_e32 v72, v120, v121
	s_waitcnt lgkmcnt(2)
	v_fma_f32 v73, v1, v112, v110
	v_mov_b32_e32 v76, v117
	v_mov_b32_e32 v77, v111
	v_mul_f32_e32 v1, v72, v116
	v_pk_fma_f32 v[72:73], v[72:73], v[74:75], v[76:77]
	v_mul_f32_e32 v78, v1, v117
	v_mov_b32_e32 v79, v73
	v_mov_b32_e32 v72, v112
	s_waitcnt lgkmcnt(1)
	v_mov_b32_e32 v73, v108
	v_pk_mul_f32 v[74:75], v[78:79], v[72:73]
	v_mov_b32_e32 v76, v113
	v_mov_b32_e32 v80, v113
	s_waitcnt lgkmcnt(0)
	v_mov_b32_e32 v81, v2
	v_pk_mul_f32 v[74:75], v[74:75], v[76:77]
	v_pk_fma_f32 v[72:73], v[78:79], v[72:73], v[80:81]
	v_mov_b32_e32 v76, v109
	v_mov_b32_e32 v72, v74
	v_pk_mul_f32 v[74:75], v[74:75], v[108:109]
	v_mov_b32_e32 v78, v109
	v_mov_b32_e32 v79, v3
	v_pk_mul_f32 v[74:75], v[74:75], v[76:77]
	v_pk_fma_f32 v[72:73], v[72:73], v[108:109], v[78:79]
	s_nop 0
	v_mov_b32_e32 v75, v73
	v_add_u32_e32 v72, s89, v136
	ds_write_b64 v143, v[74:75]
	s_waitcnt lgkmcnt(0)
	s_barrier
	ds_read_b32 v1, v135
	ds_read2_b64 v[96:99], v72 offset0:32 offset1:64
	ds_read2_b64 v[92:95], v72 offset0:96 offset1:128
	ds_read2_b64 v[88:91], v72 offset0:160 offset1:192
	v_add_u32_e32 v73, 0x400, v72
	v_add_u32_e32 v72, 0x800, v72
	ds_read2_b64 v[84:87], v73 offset0:96 offset1:128
	ds_read2_b64 v[80:83], v72 offset0:32 offset1:64
	ds_read2_b64 v[76:79], v72 offset0:96 offset1:128
	ds_read2_b64 v[72:75], v72 offset0:160 offset1:192
	s_and_saveexec_b64 s[2:3], s[8:9]
	s_cbranch_execz .LBB0_454
	v_add_u32_e32 v154, 0, v136
	v_add_u32_e32 v154, 0x10800, v154
	ds_read_b64 v[154:155], v154
	s_waitcnt lgkmcnt(0)
	v_fmac_f32_e32 v155, v154, v1
	v_mov_b32_e32 v1, v155
